# attention loop code shrunk: pairs of flexible VALU ops between aligned MFMA/DS/VMEM instructions back to 4-byte encodings (loop 2316 -> 1996 bytes, alignment kept)
# speedup vs baseline: 1.0080x; 1.0070x over previous
; DI void attn_item(const P& p, int l, int item, char* smem) {
;     ...
;   for (int kt = -1; kt < 128; ++kt) {
;     if (kt + 1 < 128) {
;       u16* Kd = Ks + ((kt + 1) & 1) * (256 * 72);
;       u16* Vd = Kd + 2 * 64 * 72;
; #pragma unroll
;       for (int i = 0; i < 2; ++i) {
;         const int row = tid >> 3, kc = tid & 7;
;         *(u32x4*)(Kd + (i * 64 + row) * 72 + kc * 8) = kreg[i];
;       }
; #pragma unroll
;       for (int i = 0; i < 2; ++i) {
;         const int cid = tid + NT * i;
;         const int e = cid >> 3, kc = cid & 7;
;         uint2 w0; w0.x = vreg[i][0]; w0.y = vreg[i][1];
;         uint2 w1; w1.x = vreg[i][2]; w1.y = vreg[i][3];
;         u16* vd = Vd + e * 72 + (kc >> 1) * 16 + (kc & 1) * 4;
;         *(uint2*)vd = w0;
;         *(uint2*)(vd + 8) = w1;
;       }
;     }
;     if (kt + 2 < 128) {
;       const int kn = kt + 2;
; #pragma unroll
;       for (int i = 0; i < 2; ++i) kreg[i] = *(const u32x4*)(kbase + ((size_t)i * SEQ + kn * 64) * 64 + tid * 8);
; #pragma unroll
;       for (int i = 0; i < 2; ++i) {
;         const int cid = tid + NT * i;
;         const int e = cid >> 3, kc = cid & 7;
;         vreg[i] = *(const u32x4*)(vbase + (size_t)e * VTP + kn * 64 + kc * 8);
;       }
;     }
;     __builtin_amdgcn_sched_barrier(0x38F);
;     if (kt >= 0) {
;       const u16* Kc = Ks + (kt & 1) * (256 * 72);
;       const u16* Vc = Kc + 2 * 64 * 72;
;       bf16x8 kf[8];
; #pragma unroll
;       for (int i = 0; i < 8; ++i)
;         kf[i] = *(const bf16x8*)(Kc + (c * 64 + 32 * (i & 1) + li) * 72 + 16 * (i >> 1) + 8 * g);
;       u32x4 vf[16];
; #pragma unroll
;       for (int i = 0; i < 16; ++i) {
;         const int eb = i & 3, s = (i >> 2) & 1, kb = i >> 3;
;         vf[i] = *(const u32x4*)(Vc + (32 * eb + li) * 72 + 32 * kb + 16 * s + 8 * g);
;       }
;       f32x16 S[2];
; #pragma unroll
;       for (int kb = 0; kb < 2; ++kb)
; #pragma unroll
;         for (int r = 0; r < 16; ++r) S[kb][r] = negm;
; #pragma unroll
;       for (int i = 0; i < 8; ++i) S[i & 1] = MFMA(kf[i], qf[i >> 1], S[i & 1]);
;       u32x4 pk[4];
;       float sum = 0.f;
; #pragma unroll
;       for (int ch = 0; ch < 4; ++ch) {
;         const int kb = ch >> 1, s = ch & 1;
; #pragma unroll
;         for (int j2 = 0; j2 < 4; ++j2) {
;           const float p0 = __builtin_amdgcn_exp2f(S[kb][8 * s + 2 * j2]);
.Lat_loop:
	s_waitcnt lgkmcnt(4)
	v_mfma_f32_32x32x16_bf16 v[64:79], v[136:139], v[176:179], v[64:79]
	ds_read_b128 v[136:139], v151 offset:9248
	v_exp_f32_e64 v104, v104
	v_exp_f32_e32 v105, v105
	v_mfma_f32_32x32x16_bf16 v[48:63], v[152:155], v[176:179], v[48:63]
	ds_read_b128 v[152:155], v151 offset:13856
	v_exp_f32_e64 v106, v106
	v_exp_f32_e32 v107, v107
	v_cvt_pk_bf16_f32 v180, v104, v105
	s_waitcnt lgkmcnt(4)
	v_mfma_f32_32x32x16_bf16 v[32:47], v[224:227], v[176:179], v[32:47]
	ds_read_b128 v[224:227], v151 offset:64
	v_exp_f32_e32 v108, v108
	v_exp_f32_e32 v109, v109
	v_cvt_pk_bf16_f32 v181, v106, v107
	v_mfma_f32_32x32x16_bf16 v[0:15], v[244:247], v[176:179], v[0:15]
	ds_read_b128 v[244:247], v151 offset:4672
	v_exp_f32_e32 v110, v110
	v_exp_f32_e32 v111, v111
	v_cvt_pk_bf16_f32 v182, v108, v109
	v_cvt_pk_bf16_f32 v183, v110, v111
	s_nop 0
	s_waitcnt lgkmcnt(4)
	v_mfma_f32_32x32x16_bf16 v[64:79], v[128:131], v[180:183], v[64:79]
	ds_read_b128 v[128:131], v151 offset:9280
	v_exp_f32_e32 v80, v80
	v_exp_f32_e32 v81, v81
	v_mfma_f32_32x32x16_bf16 v[48:63], v[132:135], v[180:183], v[48:63]
	ds_read_b128 v[132:135], v151 offset:13888
	v_exp_f32_e64 v82, v82
	v_exp_f32_e32 v83, v83
	v_cvt_pk_bf16_f32 v184, v80, v81
	s_waitcnt lgkmcnt(4)
	v_mfma_f32_32x32x16_bf16 v[32:47], v[136:139], v[180:183], v[32:47]
	ds_read_b128 v[136:139], v151 offset:96
	v_exp_f32_e32 v84, v84
	v_exp_f32_e32 v85, v85
	v_cvt_pk_bf16_f32 v185, v82, v83
	v_mfma_f32_32x32x16_bf16 v[0:15], v[152:155], v[180:183], v[0:15]
	ds_read_b128 v[152:155], v151 offset:4704
	v_exp_f32_e32 v86, v86
	v_exp_f32_e32 v87, v87
	v_cvt_pk_bf16_f32 v186, v84, v85
	v_cvt_pk_bf16_f32 v187, v86, v87
	s_nop 0
	s_waitcnt lgkmcnt(4)
	v_mfma_f32_32x32x16_bf16 v[64:79], v[224:227], v[184:187], v[64:79]
	ds_read_b128 v[224:227], v151 offset:9312
	v_exp_f32_e32 v88, v88
	v_exp_f32_e32 v89, v89
	v_mfma_f32_32x32x16_bf16 v[48:63], v[244:247], v[184:187], v[48:63]
	ds_read_b128 v[244:247], v151 offset:13920
	v_exp_f32_e64 v90, v90
	v_exp_f32_e32 v91, v91
	v_cvt_pk_bf16_f32 v192, v88, v89
	s_waitcnt lgkmcnt(4)
	v_mfma_f32_32x32x16_bf16 v[32:47], v[128:131], v[184:187], v[32:47]
	v_exp_f32_e64 v92, v92
	v_exp_f32_e32 v93, v93
	v_cvt_pk_bf16_f32 v193, v90, v91
	s_waitcnt vmcnt(0)
	ds_write_b128 v168, v[228:231] offset:36864
	ds_write_b128 v168, v[232:235] offset:46080
	v_mfma_f32_32x32x16_bf16 v[0:15], v[132:135], v[184:187], v[0:15]
	v_exp_f32_e64 v94, v94
	v_exp_f32_e32 v95, v95
	v_cvt_pk_bf16_f32 v194, v92, v93
	v_cvt_pk_bf16_f32 v195, v94, v95
	s_nop 0
	ds_write_b64 v169, v[236:237] offset:55296
	ds_write_b64 v169, v[238:239] offset:55312
	s_waitcnt lgkmcnt(6)
	v_mfma_f32_32x32x16_bf16 v[64:79], v[136:139], v[192:195], v[64:79]
	v_add_f32_e32 v167, v167, v104
	v_add_f32_e32 v190, v190, v105
	v_add_f32_e64 v191, v191, v106
	v_add_f32_e32 v196, v196, v107
	ds_write_b64 v143, v[240:241] offset:55296
	ds_write_b64 v143, v[242:243] offset:55312
	v_mfma_f32_32x32x16_bf16 v[48:63], v[152:155], v[192:195], v[48:63]
	v_add_f32_e32 v167, v167, v108
	v_add_f32_e32 v190, v190, v109
	v_add_f32_e64 v191, v191, v110
	v_add_f32_e32 v196, v196, v111
	s_waitcnt lgkmcnt(6)
	v_mfma_f32_32x32x16_bf16 v[32:47], v[224:227], v[192:195], v[32:47]
	v_add_f32_e32 v167, v167, v80
	v_add_f32_e32 v190, v190, v81
	v_add_f32_e32 v191, v191, v82
	v_add_f32_e32 v196, v196, v83
	v_mfma_f32_32x32x16_bf16 v[0:15], v[244:247], v[192:195], v[0:15]
	v_add_f32_e32 v167, v167, v84
	v_add_f32_e32 v190, v190, v85
	v_add_f32_e32 v191, v191, v86
	v_add_f32_e32 v196, v196, v87
	s_waitcnt lgkmcnt(0)
	s_barrier
	ds_read_b128 v[128:131], v150 offset:36864
	ds_read_b128 v[132:135], v150 offset:36896
	ds_read_b128 v[136:139], v150 offset:36928
	ds_read_b128 v[152:155], v150 offset:36960
	ds_read_b128 v[224:227], v150 offset:41472
	ds_read_b128 v[244:247], v150 offset:41504
	global_load_dwordx4 v[232:235], v148, s[98:99]
	global_load_dwordx4 v[228:231], v156, s[98:99]
	global_load_dwordx4 v[236:239], v146, s[100:101]
	global_load_dwordx4 v[240:243], v144, s[100:101]
	s_waitcnt lgkmcnt(4)
	v_mfma_f32_32x32x16_bf16 v[96:111], v[128:131], v[112:115], v[16:31]
	ds_read_b128 v[128:131], v150 offset:41536
	v_add_f32_e64 v167, v167, v88
	v_add_f32_e32 v190, v190, v89
	v_mfma_f32_32x32x16_bf16 v[96:111], v[132:135], v[116:119], v[96:111]
	ds_read_b128 v[132:135], v150 offset:41568
	v_add_f32_e64 v191, v191, v90
	v_add_f32_e32 v196, v196, v91
	s_waitcnt lgkmcnt(4)
	v_mfma_f32_32x32x16_bf16 v[96:111], v[136:139], v[124:127], v[96:111]
	ds_read_b128 v[136:139], v151 offset:36864
	v_add_f32_e32 v167, v167, v92
	v_add_f32_e32 v190, v190, v93
	v_mfma_f32_32x32x16_bf16 v[96:111], v[152:155], v[120:123], v[96:111]
	ds_read_b128 v[152:155], v151 offset:41472
	v_add_f32_e64 v191, v191, v94
	v_add_f32_e32 v196, v196, v95
	s_add_u32 s98, s98, s14
	s_addc_u32 s99, s99, s15
	s_waitcnt lgkmcnt(4)
	v_mfma_f32_32x32x16_bf16 v[80:95], v[224:227], v[112:115], v[16:31]
	ds_read_b128 v[224:227], v151 offset:46080
	s_add_u32 s100, s100, s58
	s_addc_u32 s101, s101, s59
	v_mfma_f32_32x32x16_bf16 v[80:95], v[244:247], v[116:119], v[80:95]
	ds_read_b128 v[244:247], v151 offset:50688
	s_nop 2
	v_exp_f32_e32 v96, v96
	v_exp_f32_e32 v97, v97
	s_waitcnt lgkmcnt(4)
	v_mfma_f32_32x32x16_bf16 v[80:95], v[128:131], v[124:127], v[80:95]
	ds_read_b128 v[128:131], v151 offset:36896
	v_exp_f32_e32 v98, v98
	v_exp_f32_e32 v99, v99
	v_exp_f32_e64 v100, v100
	v_mfma_f32_32x32x16_bf16 v[80:95], v[132:135], v[120:123], v[80:95]
	ds_read_b128 v[132:135], v151 offset:41504
	v_exp_f32_e32 v101, v101
	v_exp_f32_e32 v102, v102
	v_exp_f32_e32 v103, v103
	v_add_f32_e32 v167, v167, v96
	v_add_f32_e32 v190, v190, v97
	v_add_f32_e32 v191, v191, v98
	v_cvt_pk_bf16_f32 v176, v96, v97
	v_cvt_pk_bf16_f32 v177, v98, v99
	v_cvt_pk_bf16_f32 v178, v100, v101
	v_cvt_pk_bf16_f32 v179, v102, v103
	v_add_f32_e32 v196, v196, v99
	v_add_f32_e32 v167, v167, v100
	v_add_f32_e32 v190, v190, v101
	v_add_f32_e32 v191, v191, v102
	v_add_f32_e32 v196, v196, v103
	s_waitcnt lgkmcnt(4)
; DI void attn_item(const P& p, int l, int item, char* smem) {
;     ...
;   for (int kt = -1; kt < 128; ++kt) {
;     if (kt + 1 < 128) {
;       u16* Kd = Ks + ((kt + 1) & 1) * (256 * 72);
;       u16* Vd = Kd + 2 * 64 * 72;
; #pragma unroll
;       for (int i = 0; i < 2; ++i) {
;         const int row = tid >> 3, kc = tid & 7;
;         *(u32x4*)(Kd + (i * 64 + row) * 72 + kc * 8) = kreg[i];
;       }
; #pragma unroll
;       for (int i = 0; i < 2; ++i) {
;         const int cid = tid + NT * i;
;         const int e = cid >> 3, kc = cid & 7;
;         uint2 w0; w0.x = vreg[i][0]; w0.y = vreg[i][1];
;         uint2 w1; w1.x = vreg[i][2]; w1.y = vreg[i][3];
;         u16* vd = Vd + e * 72 + (kc >> 1) * 16 + (kc & 1) * 4;
;         *(uint2*)vd = w0;
;         *(uint2*)(vd + 8) = w1;
;       }
;     }
;     if (kt + 2 < 128) {
;       const int kn = kt + 2;
; #pragma unroll
;       for (int i = 0; i < 2; ++i) kreg[i] = *(const u32x4*)(kbase + ((size_t)i * SEQ + kn * 64) * 64 + tid * 8);
; #pragma unroll
;       for (int i = 0; i < 2; ++i) {
;         const int cid = tid + NT * i;
;         const int e = cid >> 3, kc = cid & 7;
;         vreg[i] = *(const u32x4*)(vbase + (size_t)e * VTP + kn * 64 + kc * 8);
;       }
;     }
;     __builtin_amdgcn_sched_barrier(0x38F);
;     if (kt >= 0) {
;       const u16* Kc = Ks + (kt & 1) * (256 * 72);
;       const u16* Vc = Kc + 2 * 64 * 72;
;       bf16x8 kf[8];
; #pragma unroll
;       for (int i = 0; i < 8; ++i)
;         kf[i] = *(const bf16x8*)(Kc + (c * 64 + 32 * (i & 1) + li) * 72 + 16 * (i >> 1) + 8 * g);
;       u32x4 vf[16];
; #pragma unroll
;       for (int i = 0; i < 16; ++i) {
;         const int eb = i & 3, s = (i >> 2) & 1, kb = i >> 3;
;         vf[i] = *(const u32x4*)(Vc + (32 * eb + li) * 72 + 32 * kb + 16 * s + 8 * g);
;       }
;       f32x16 S[2];
; #pragma unroll
;       for (int kb = 0; kb < 2; ++kb)
; #pragma unroll
;         for (int r = 0; r < 16; ++r) S[kb][r] = negm;
; #pragma unroll
;       for (int i = 0; i < 8; ++i) S[i & 1] = MFMA(kf[i], qf[i >> 1], S[i & 1]);
;       u32x4 pk[4];
;       float sum = 0.f;
; #pragma unroll
;       for (int ch = 0; ch < 4; ++ch) {
;         const int kb = ch >> 1, s = ch & 1;
; #pragma unroll
;         for (int j2 = 0; j2 < 4; ++j2) {
;           const float p0 = __builtin_amdgcn_exp2f(S[kb][8 * s + 2 * j2]);
	v_mfma_f32_32x32x16_bf16 v[64:79], v[136:139], v[176:179], v[64:79]
	ds_read_b128 v[136:139], v151 offset:46112
	v_exp_f32_e32 v104, v104
	v_exp_f32_e32 v105, v105
	v_mfma_f32_32x32x16_bf16 v[48:63], v[152:155], v[176:179], v[48:63]
	ds_read_b128 v[152:155], v151 offset:50720
	v_exp_f32_e64 v106, v106
	v_exp_f32_e32 v107, v107
	v_cvt_pk_bf16_f32 v180, v104, v105
	s_waitcnt lgkmcnt(4)
	v_mfma_f32_32x32x16_bf16 v[32:47], v[224:227], v[176:179], v[32:47]
	ds_read_b128 v[224:227], v151 offset:36928
	v_exp_f32_e32 v108, v108
	v_exp_f32_e32 v109, v109
	v_cvt_pk_bf16_f32 v181, v106, v107
	v_mfma_f32_32x32x16_bf16 v[0:15], v[244:247], v[176:179], v[0:15]
	ds_read_b128 v[244:247], v151 offset:41536
	v_exp_f32_e32 v110, v110
	v_exp_f32_e32 v111, v111
	v_cvt_pk_bf16_f32 v182, v108, v109
	v_cvt_pk_bf16_f32 v183, v110, v111
	s_nop 0
	s_waitcnt lgkmcnt(4)
	v_mfma_f32_32x32x16_bf16 v[64:79], v[128:131], v[180:183], v[64:79]
	ds_read_b128 v[128:131], v151 offset:46144
	v_exp_f32_e32 v80, v80
	v_exp_f32_e32 v81, v81
	v_mfma_f32_32x32x16_bf16 v[48:63], v[132:135], v[180:183], v[48:63]
	ds_read_b128 v[132:135], v151 offset:50752
	v_exp_f32_e64 v82, v82
	v_exp_f32_e32 v83, v83
	v_cvt_pk_bf16_f32 v184, v80, v81
	s_waitcnt lgkmcnt(4)
	v_mfma_f32_32x32x16_bf16 v[32:47], v[136:139], v[180:183], v[32:47]
	ds_read_b128 v[136:139], v151 offset:36960
	v_exp_f32_e32 v84, v84
	v_exp_f32_e32 v85, v85
	v_cvt_pk_bf16_f32 v185, v82, v83
	v_mfma_f32_32x32x16_bf16 v[0:15], v[152:155], v[180:183], v[0:15]
	ds_read_b128 v[152:155], v151 offset:41568
	v_exp_f32_e32 v86, v86
	v_exp_f32_e32 v87, v87
	v_cvt_pk_bf16_f32 v186, v84, v85
	v_cvt_pk_bf16_f32 v187, v86, v87
	s_nop 0
	s_waitcnt lgkmcnt(4)
	v_mfma_f32_32x32x16_bf16 v[64:79], v[224:227], v[184:187], v[64:79]
	ds_read_b128 v[224:227], v151 offset:46176
	v_exp_f32_e32 v88, v88
	v_exp_f32_e32 v89, v89
	v_mfma_f32_32x32x16_bf16 v[48:63], v[244:247], v[184:187], v[48:63]
	ds_read_b128 v[244:247], v151 offset:50784
	v_exp_f32_e64 v90, v90
	v_exp_f32_e32 v91, v91
	v_cvt_pk_bf16_f32 v192, v88, v89
	s_waitcnt lgkmcnt(4)
	v_mfma_f32_32x32x16_bf16 v[32:47], v[128:131], v[184:187], v[32:47]
	v_exp_f32_e64 v92, v92
	v_exp_f32_e32 v93, v93
	v_cvt_pk_bf16_f32 v193, v90, v91
	s_waitcnt vmcnt(0)
	ds_write_b128 v168, v[228:231] offset:0
	ds_write_b128 v168, v[232:235] offset:9216
	v_mfma_f32_32x32x16_bf16 v[0:15], v[132:135], v[184:187], v[0:15]
	v_exp_f32_e64 v94, v94
	v_exp_f32_e32 v95, v95
	v_cvt_pk_bf16_f32 v194, v92, v93
	v_cvt_pk_bf16_f32 v195, v94, v95
	s_nop 0
	ds_write_b64 v169, v[236:237] offset:18432
	ds_write_b64 v169, v[238:239] offset:18448
	s_waitcnt lgkmcnt(6)
	v_mfma_f32_32x32x16_bf16 v[64:79], v[136:139], v[192:195], v[64:79]
	v_add_f32_e32 v167, v167, v104
	v_add_f32_e32 v190, v190, v105
	v_add_f32_e64 v191, v191, v106
	v_add_f32_e32 v196, v196, v107
	ds_write_b64 v143, v[240:241] offset:18432
	ds_write_b64 v143, v[242:243] offset:18448
	v_mfma_f32_32x32x16_bf16 v[48:63], v[152:155], v[192:195], v[48:63]
	v_add_f32_e32 v167, v167, v108
	v_add_f32_e32 v190, v190, v109
	v_add_f32_e64 v191, v191, v110
	v_add_f32_e32 v196, v196, v111
	s_waitcnt lgkmcnt(6)
	v_mfma_f32_32x32x16_bf16 v[32:47], v[224:227], v[192:195], v[32:47]
	v_add_f32_e32 v167, v167, v80
	v_add_f32_e32 v190, v190, v81
	v_add_f32_e32 v191, v191, v82
	v_add_f32_e32 v196, v196, v83
	v_mfma_f32_32x32x16_bf16 v[0:15], v[244:247], v[192:195], v[0:15]
	v_add_f32_e32 v167, v167, v84
	v_add_f32_e32 v190, v190, v85
	v_add_f32_e64 v191, v191, v86
	v_add_f32_e32 v196, v196, v87
	s_waitcnt lgkmcnt(0)
	s_barrier
	s_add_i32 s10, s10, -1
	s_cmp_eq_u32 s10, 0
	s_cbranch_scc1 .Lat_exit
	ds_read_b128 v[128:131], v150 offset:0
	ds_read_b128 v[132:135], v150 offset:32
	ds_read_b128 v[136:139], v150 offset:64
	ds_read_b128 v[152:155], v150 offset:96
	ds_read_b128 v[224:227], v150 offset:4608
	ds_read_b128 v[244:247], v150 offset:4640
	global_load_dwordx4 v[232:235], v148, s[98:99]
	global_load_dwordx4 v[228:231], v156, s[98:99]
	global_load_dwordx4 v[236:239], v146, s[100:101]
	global_load_dwordx4 v[240:243], v144, s[100:101]
	s_waitcnt lgkmcnt(4)
	v_mfma_f32_32x32x16_bf16 v[96:111], v[128:131], v[112:115], v[16:31]
	ds_read_b128 v[128:131], v150 offset:4672
	v_add_f32_e64 v167, v167, v88
	v_add_f32_e32 v190, v190, v89
	v_mfma_f32_32x32x16_bf16 v[96:111], v[132:135], v[116:119], v[96:111]
	ds_read_b128 v[132:135], v150 offset:4704
	v_add_f32_e64 v191, v191, v90
	v_add_f32_e32 v196, v196, v91
	s_waitcnt lgkmcnt(4)
	v_mfma_f32_32x32x16_bf16 v[96:111], v[136:139], v[124:127], v[96:111]
	ds_read_b128 v[136:139], v151 offset:0
	v_add_f32_e32 v167, v167, v92
	v_add_f32_e32 v190, v190, v93
	v_mfma_f32_32x32x16_bf16 v[96:111], v[152:155], v[120:123], v[96:111]
	ds_read_b128 v[152:155], v151 offset:4608
	v_add_f32_e64 v191, v191, v94
	v_add_f32_e32 v196, v196, v95
	s_add_u32 s98, s98, s14
	s_addc_u32 s99, s99, s15
	s_waitcnt lgkmcnt(4)
	v_mfma_f32_32x32x16_bf16 v[80:95], v[224:227], v[112:115], v[16:31]
	ds_read_b128 v[224:227], v151 offset:9216
	s_add_u32 s100, s100, s58
	s_addc_u32 s101, s101, s59
	v_mfma_f32_32x32x16_bf16 v[80:95], v[244:247], v[116:119], v[80:95]
	ds_read_b128 v[244:247], v151 offset:13824
	s_nop 2
	v_exp_f32_e32 v96, v96
	v_exp_f32_e32 v97, v97
	s_waitcnt lgkmcnt(4)
	v_mfma_f32_32x32x16_bf16 v[80:95], v[128:131], v[124:127], v[80:95]
	ds_read_b128 v[128:131], v151 offset:32
	v_exp_f32_e32 v98, v98
	v_exp_f32_e32 v99, v99
	v_exp_f32_e64 v100, v100
	v_mfma_f32_32x32x16_bf16 v[80:95], v[132:135], v[120:123], v[80:95]
	ds_read_b128 v[132:135], v151 offset:4640
	v_exp_f32_e32 v101, v101
	v_exp_f32_e32 v102, v102
	v_exp_f32_e32 v103, v103
	v_add_f32_e32 v167, v167, v96
	v_add_f32_e32 v190, v190, v97
	v_add_f32_e32 v191, v191, v98
	v_cvt_pk_bf16_f32 v176, v96, v97
	v_cvt_pk_bf16_f32 v177, v98, v99
	v_cvt_pk_bf16_f32 v178, v100, v101
	v_cvt_pk_bf16_f32 v179, v102, v103
	v_add_f32_e32 v196, v196, v99
	v_add_f32_e32 v167, v167, v100
	v_add_f32_e32 v190, v190, v101
	v_add_f32_e32 v191, v191, v102
	v_add_f32_e64 v196, v196, v103
	s_branch .Lat_loop
